# pool mixer takes the per-row RMS from the stored per-row sum-of-squares partials (same f32 statistic the GEMM prologues use) instead of re-reading 47 window rows per tile
# speedup vs baseline: 1.0118x; 1.0079x over previous
.LBB0_1218:
	s_lshl_b32 s0, s12, 5
	s_and_b32 s14, s0, 0xfe0
	s_barrier
	v_readfirstlane_b32 s26, v12
	v_readlane_b32 s22, v250, 9
	v_readlane_b32 s23, v250, 10
	v_readlane_b32 s38, v250, 11
	v_readlane_b32 s39, v250, 12
	s_add_u32 s38, s38, 0xf900000
	s_addc_u32 s39, s39, 0
	s_add_i32 s28, s13, s26
	s_sub_i32 s28, s28, 15
	s_ashr_i32 s29, s28, 31
	s_lshl_b64 s[24:25], s[28:29], 6
	s_add_u32 s38, s38, s24
	s_addc_u32 s39, s39, s25
	v_lshrrev_b32_e32 v232, 2, v214
	v_lshl_add_u32 v233, v232, 2, s26
	v_lshl_add_u32 v234, v232, 2, s28
	v_cmp_gt_i32_e64 s[30:31], 47, v233
	v_cmp_le_i32_e32 vcc, 0, v234
	s_and_b64 s[30:31], s[30:31], vcc
	v_and_b32_e32 v235, 3, v214
	v_lshlrev_b32_e32 v235, 4, v235
	v_lshl_or_b32 v235, v232, 8, v235
	s_and_saveexec_b64 s[36:37], s[30:31]
	global_load_dwordx4 v[236:239], v235, s[38:39]
	s_mov_b64 exec, s[36:37]
	v_lshlrev_b32_e32 v221, 4, v205
	v_lshlrev_b32_e32 v222, 3, v205
	s_sub_i32 s28, s13, 15
	s_ashr_i32 s29, s28, 31
	s_lshl_b64 s[24:25], s[28:29], 12
	s_add_u32 s24, s22, s24
	s_addc_u32 s25, s23, s25
	v_readfirstlane_b32 s27, v13
	s_sub_i32 s27, 16, s27
	s_cmp_eq_u32 s14, 0
	s_cselect_b32 s27, 15, s27
	s_cmp_gt_u32 s27, 0
	s_cbranch_scc1 .Lpool_ldskip_0
	global_load_dwordx4 v[20:23], v221, s[24:25]

.Lpool_ldskip_14:
	s_add_u32 s24, s24, 0x1000
	s_addc_u32 s25, s25, 0
	global_load_dwordx4 v[80:83], v221, s[24:25]
	s_add_u32 s24, s24, 0x1000
	s_addc_u32 s25, s25, 0
	global_load_dwordx4 v[84:87], v221, s[24:25]
	s_add_u32 s24, s24, 0x1000
	s_addc_u32 s25, s25, 0
	global_load_dwordx4 v[88:91], v221, s[24:25]
	s_add_u32 s24, s24, 0x1000
	s_addc_u32 s25, s25, 0
	global_load_dwordx4 v[92:95], v221, s[24:25]
	s_add_u32 s24, s24, 0x1000
	s_addc_u32 s25, s25, 0
	global_load_dwordx4 v[96:99], v221, s[24:25]
	s_add_u32 s24, s24, 0x1000
	s_addc_u32 s25, s25, 0
	global_load_dwordx4 v[100:103], v221, s[24:25]
	s_add_u32 s24, s24, 0x1000
	s_addc_u32 s25, s25, 0
	global_load_dwordx4 v[104:107], v221, s[24:25]
	s_add_u32 s24, s24, 0x1000
	s_addc_u32 s25, s25, 0
	global_load_dwordx4 v[108:111], v221, s[24:25]
	s_add_u32 s24, s24, 0x1000
	s_addc_u32 s25, s25, 0
	global_load_dwordx4 v[112:115], v221, s[24:25]
	s_add_u32 s24, s24, 0x1000
	s_addc_u32 s25, s25, 0
	global_load_dwordx4 v[116:119], v221, s[24:25]
	s_add_u32 s24, s24, 0x1000
	s_addc_u32 s25, s25, 0
	global_load_dwordx4 v[120:123], v221, s[24:25]
	s_add_u32 s24, s24, 0x1000
	s_addc_u32 s25, s25, 0
	global_load_dwordx4 v[124:127], v221, s[24:25]
	s_add_u32 s24, s24, 0x1000
	s_addc_u32 s25, s25, 0
	global_load_dwordx4 v[128:131], v221, s[24:25]
	s_add_u32 s24, s24, 0x1000
	s_addc_u32 s25, s25, 0
	global_load_dwordx4 v[132:135], v221, s[24:25]
	s_add_u32 s24, s24, 0x1000
	s_addc_u32 s25, s25, 0
	global_load_dwordx4 v[136:139], v221, s[24:25]
	s_add_u32 s24, s24, 0x1000
	s_addc_u32 s25, s25, 0
	global_load_dwordx4 v[140:143], v221, s[24:25]
	s_add_u32 s24, s24, 0x1000
	s_addc_u32 s25, s25, 0
	global_load_dwordx4 v[144:147], v221, s[24:25]
	s_add_u32 s24, s24, 0x1000
	s_addc_u32 s25, s25, 0
	global_load_dwordx4 v[148:151], v221, s[24:25]
	s_add_u32 s24, s24, 0x1000
	s_addc_u32 s25, s25, 0
	global_load_dwordx4 v[152:155], v221, s[24:25]
	s_add_u32 s24, s24, 0x1000
	s_addc_u32 s25, s25, 0
	global_load_dwordx4 v[156:159], v221, s[24:25]
	s_add_u32 s24, s24, 0x1000
	s_addc_u32 s25, s25, 0
	global_load_dwordx4 v[160:163], v221, s[24:25]
	s_add_u32 s24, s24, 0x1000
	s_addc_u32 s25, s25, 0
	global_load_dwordx4 v[164:167], v221, s[24:25]
	s_add_u32 s24, s24, 0x1000
	s_addc_u32 s25, s25, 0
	global_load_dwordx4 v[168:171], v221, s[24:25]
	s_add_u32 s24, s24, 0x1000
	s_addc_u32 s25, s25, 0
	global_load_dwordx4 v[172:175], v221, s[24:25]
	s_add_u32 s24, s24, 0x1000
	s_addc_u32 s25, s25, 0
	global_load_dwordx4 v[176:179], v221, s[24:25]
	s_add_u32 s24, s24, 0x1000
	s_addc_u32 s25, s25, 0
	global_load_dwordx4 v[180:183], v221, s[24:25]
	s_add_u32 s24, s24, 0x1000
	s_addc_u32 s25, s25, 0
	global_load_dwordx4 v[184:187], v221, s[24:25]
	s_add_u32 s24, s24, 0x1000
	s_addc_u32 s25, s25, 0
	global_load_dwordx4 v[188:191], v221, s[24:25]
	s_add_u32 s24, s24, 0x1000
	s_addc_u32 s25, s25, 0
	global_load_dwordx4 v[192:195], v221, s[24:25]
	s_add_u32 s24, s24, 0x1000
	s_addc_u32 s25, s25, 0
	global_load_dwordx4 v[196:199], v221, s[24:25]
	s_add_u32 s24, s24, 0x1000
	s_addc_u32 s25, s25, 0
	global_load_dwordx4 v[200:203], v221, s[24:25]
	s_add_u32 s24, s24, 0x1000
	s_addc_u32 s25, s25, 0
	global_load_dwordx4 v[216:219], v221, s[24:25]
	s_waitcnt vmcnt(32)
	v_add_f32_e32 v236, v236, v237
	v_add_f32_e32 v238, v238, v239
	v_add_f32_e32 v236, v236, v238
	s_nop 1
	v_add_f32_dpp v236, v236, v236 quad_perm:[1,0,3,2] row_mask:0xf bank_mask:0xf
	s_nop 1
	v_add_f32_dpp v236, v236, v236 quad_perm:[2,3,0,1] row_mask:0xf bank_mask:0xf
	v_fmamk_f32 v236, v236, 0x3a800000, v206
	v_mul_f32_e32 v237, 0x4b800000, v236
	v_cmp_gt_f32_e32 vcc, s58, v236
	s_nop 1
	v_cndmask_b32_e32 v236, v236, v237, vcc
	v_rsq_f32_e32 v236, v236
	s_nop 0
	v_mul_f32_e32 v237, 0x45800000, v236
	v_cndmask_b32_e32 v236, v236, v237, vcc
	v_mov_b32_e32 v223, s80
	v_lshl_add_u32 v0, v233, 2, v223
	v_and_b32_e32 v238, 3, v214
	v_cmp_eq_u32_e32 vcc, 0, v238
	s_and_b64 s[30:31], s[30:31], vcc
	s_and_saveexec_b64 s[36:37], s[30:31]
	ds_write_b32 v0, v236
	s_mov_b64 exec, s[36:37]
	s_waitcnt lgkmcnt(0)
	s_barrier
	v_readlane_b32 s34, v250, 48
	v_readlane_b32 s35, v250, 49
	s_ashr_i32 s29, s13, 31
	s_mov_b32 s28, s13
	s_lshl_b64 s[28:29], s[28:29], 11
	s_add_u32 s34, s34, s28
	s_addc_u32 s35, s35, s29
	s_cmp_eq_u32 s26, 0
	s_cbranch_scc1 .Lpool_v0
	s_cmp_eq_u32 s26, 1
	s_cbranch_scc1 .Lpool_v1
	s_cmp_eq_u32 s26, 2
	s_cbranch_scc1 .Lpool_v2
	s_branch .Lpool_v3
